# MLA loop: K/V tile addresses kept as running 32-bit offsets from the workspace base (per-lane stride, one correction at the latent->context switch) instead of recomputing 64-bit addresses behind lane-
# baseline (speedup 1.0000x reference)
; template <int DQK>
; DI void attn_tile(const u16* __restrict__ q, int ldq, int qpos0, const Seg& s0, const Seg& s1, int nseg, bool has_sink,
;                   float sinkl2, u16* __restrict__ out, int ldo, char* lds) {
;     ...
;   bf16x8 qf[NKS];
; #pragma unroll
;   for (int ks = 0; ks < NKS; ++ks) qf[ks] = *(const bf16x8*)(q + (size_t)qi * ldq + ks * 16 + 8 * h);
;   const int nt0 = s0.n >> 6;
;   const int NT = nt0 + (nseg > 1 ? (s1.n >> 6) : 0);
;   uint4 kreg0, kreg1 = make_uint4(0, 0, 0, 0), vreg0;
;   uint4 krgB0, krgB1 = make_uint4(0, 0, 0, 0), vrgB0;
;   const int kkey0 = ltid / CPK, kpart0 = ltid % CPK;
;   const int kkey1 = (ltid + 512) / CPK, kpart1 = (ltid + 512) % CPK;
;   const bool k1 = (CPK == 12) && (ltid < 256);
;   const int vkey = ltid >> 3, vpart = ltid & 7;
;   typedef __attribute__((address_space(3))) const char* lds_cptr;
;   typedef short v4i16_t __attribute__((ext_vector_type(4)));
;   const lds_cptr vp0 = (lds_cptr)Vs + (4 * h + ((lane & 15) >> 2)) * (VST * 2) + ((lane >> 4) & 1) * 32 + (lane & 3) * 8;
; DI void mla_attn(const Params& p, int idx, char* lds) {
;     ...
;   const size_t lr = (size_t)b * TT, cr = (size_t)NLAT + b * LC;
;   lat.k = KVD + lr * KVP + hh * 128; lat.ldk = KVP; lat.k2 = KR + lr * 32; lat.ldk2 = 32; lat.v = KVD + lr * KVP + hh * 128 + 64;
;   lat.ldv = KVP; lat.n = TT; lat.pos0 = 0; lat.masked = 0;
;   cx.k = KVD + cr * KVP + hh * 128; cx.ldk = KVP; cx.k2 = KR + cr * 32; cx.ldk2 = 32; cx.v = KVD + cr * KVP + hh * 128 + 64;
;   cx.ldv = KVP; cx.n = LC; cx.pos0 = 0; cx.masked = 0;
;   const u16* q = QD + (size_t)row0 * 384 + hh * 96;
;   u16* o = act + (size_t)row0 * AP + 768 + hh * 64;
.LBB0_576:
	s_and_b32 s1, s1, 3
	v_readlane_b32 s10, v252, 20
	s_lshl_b32 s21, s1, 7
	s_mul_i32 s5, s10, 0x480
	v_readlane_b32 s6, v250, 57
	s_mul_hi_u32 s4, s10, 0x480
	s_add_u32 s5, s6, s5
	v_readlane_b32 s6, v250, 58
	s_addc_u32 s4, s6, s4
	s_lshl_b32 s6, s1, 8
	v_readlane_b32 s11, v252, 21
	s_add_u32 s8, s5, s6
	s_addc_u32 s9, s4, 0
	s_lshl_b64 s[4:5], s[10:11], 6
	v_readlane_b32 s6, v250, 61
	v_readlane_b32 s7, v250, 62
	s_add_u32 s10, s6, s4
	s_addc_u32 s11, s7, s5
	s_mul_i32 s5, s20, 0x300
	v_readlane_b32 s6, v251, 1
	s_mul_hi_u32 s4, s20, 0x300
	s_add_u32 s5, s6, s5
	v_readlane_b32 s6, v251, 2
	s_addc_u32 s4, s6, s4
	s_mulk_i32 s1, 0xc0
	s_add_u32 s6, s5, s1
	s_addc_u32 s7, s4, 0
	s_andn2_b64 vcc, exec, s[2:3]
	s_mov_b64 s[2:3], -1
	s_cbranch_vccnz .LBB0_728
	v_mov_b32_e32 v7, v165
	s_movk_i32 s1, 0x60
	v_and_b32_e32 v6, 31, v7
	v_lshrrev_b32_e32 v0, 1, v7
	v_and_or_b32 v115, v0, s1, v6
	v_bfe_u32 v8, v7, 5, 1
	v_mul_u32_u24_e32 v0, 0x300, v115
	v_lshl_add_u64 v[2:3], s[6:7], 0, v[0:1]
	v_lshlrev_b32_e32 v0, 4, v8
	v_lshl_add_u64 v[2:3], v[2:3], 0, v[0:1]
	global_load_dwordx4 v[66:69], v[2:3], off
	global_load_dwordx4 v[70:73], v[2:3], off offset:32
	global_load_dwordx4 v[74:77], v[2:3], off offset:64
	global_load_dwordx4 v[78:81], v[2:3], off offset:96
	global_load_dwordx4 v[82:85], v[2:3], off offset:128
	global_load_dwordx4 v[86:89], v[2:3], off offset:160
	v_readlane_b32 s2, v252, 20
	v_readlane_b32 s3, v252, 21
	s_mov_b32 s1, s3
	s_mul_i32 s3, s0, 0x480000
	v_readlane_b32 s4, v250, 57
	s_mul_hi_u32 s2, s0, 0x480000
	s_add_u32 s3, s4, s3
	v_readlane_b32 s4, v250, 58
	s_addc_u32 s2, s4, s2
	s_lshl_b32 s4, s21, 1
	s_add_u32 s12, s3, s4
	s_addc_u32 s13, s2, 0
	s_lshl_b64 s[0:1], s[0:1], 18
	v_readlane_b32 s2, v250, 61
	s_add_u32 s14, s2, s0
	s_mov_b32 s0, 0x2aaaaaab
	v_mul_hi_i32 v0, v7, s0
	v_lshrrev_b32_e32 v2, 31, v0
	v_ashrrev_i32_e32 v0, 1, v0
	v_add_u32_e32 v116, v0, v2
	v_mul_lo_u32 v0, v116, 12
	v_readlane_b32 s3, v250, 62
	v_sub_u32_e32 v0, v7, v0
	s_addc_u32 s15, s3, s1
	v_cmp_lt_i32_e32 vcc, 7, v0
	v_ashrrev_i32_e32 v117, 31, v116
	v_lshlrev_b32_e32 v118, 3, v0
	s_and_saveexec_b64 s[0:1], vcc
	s_xor_b64 s[0:1], exec, s[0:1]
	v_lshlrev_b64 v[2:3], 6, v[116:117]
	v_lshl_add_u64 v[2:3], s[14:15], 0, v[2:3]
	v_mov_b32_e32 v119, v1
	s_movk_i32 s2, 0xff80
	v_lshl_add_u64 v[2:3], v[118:119], 1, v[2:3]
	s_mov_b32 s3, -1
	v_lshl_add_u64 v[2:3], v[2:3], 0, s[2:3]
	s_or_saveexec_b64 s[0:1], s[0:1]
	v_ashrrev_i32_e32 v119, 31, v118
	s_xor_b64 exec, exec, s[0:1]
	v_mov_b64_e32 v[2:3], s[12:13]
	v_mad_i64_i32 v[2:3], s[2:3], v116, s61, v[2:3]
	v_lshl_add_u64 v[2:3], v[118:119], 1, v[2:3]
	s_or_b64 exec, exec, s[0:1]
	global_load_dwordx4 v[90:93], v[2:3], off
	v_subrev_u32_e32 v138, s84, v2
	v_add_u32_e32 v0, 0x200, v7
	s_mov_b32 s0, 0x2aaaaaab
	v_mul_hi_i32 v2, v0, s0
	v_lshrrev_b32_e32 v3, 31, v2
	v_ashrrev_i32_e32 v2, 1, v2
	v_add_u32_e32 v120, v2, v3
	v_mul_lo_u32 v2, v120, 12
	s_movk_i32 s0, 0xff
	v_sub_u32_e32 v9, v0, v2
	v_cmp_lt_i32_e64 s[2:3], s0, v7
	s_movk_i32 s0, 0x100
	v_mov_b32_e32 v0, v1
	v_cmp_gt_i32_e64 s[0:1], s0, v7
	v_lshlrev_b32_e32 v122, 3, v9
	v_mov_b64_e32 v[96:97], v[0:1]
	v_mov_b64_e32 v[94:95], v[0:1]
	s_and_saveexec_b64 s[16:17], s[0:1]
	s_cbranch_execz .LBB0_587
	v_cmp_lt_i32_e64 s[4:5], 7, v9
	v_ashrrev_i32_e32 v121, 31, v120
	v_lshlrev_b32_e32 v2, 3, v9
	s_and_saveexec_b64 s[18:19], s[4:5]
	s_xor_b64 s[4:5], exec, s[18:19]
	v_lshlrev_b64 v[4:5], 6, v[120:121]
	v_lshl_add_u64 v[4:5], s[14:15], 0, v[4:5]
	v_mov_b32_e32 v3, v1
	s_movk_i32 s18, 0xff80
	v_lshl_add_u64 v[2:3], v[2:3], 1, v[4:5]
	s_mov_b32 s19, -1
	v_lshl_add_u64 v[4:5], v[2:3], 0, s[18:19]
	s_andn2_saveexec_b64 s[4:5], s[4:5]
	v_mov_b64_e32 v[4:5], s[12:13]
	v_mad_i64_i32 v[4:5], s[18:19], v120, s61, v[4:5]
	v_ashrrev_i32_e32 v3, 31, v2
	v_lshl_add_u64 v[4:5], v[2:3], 1, v[4:5]
	s_or_b64 exec, exec, s[4:5]
	global_load_dwordx4 v[94:97], v[4:5], off
	v_subrev_u32_e32 v142, s84, v4
.LBB0_587:
	s_or_b64 exec, exec, s[16:17]
	v_lshlrev_b32_e32 v11, 3, v7
	v_ashrrev_i32_e32 v117, 3, v7
	v_mov_b64_e32 v[2:3], s[12:13]
	v_and_b32_e32 v0, 56, v11
	v_mad_i64_i32 v[2:3], s[4:5], v117, s61, v[2:3]
	v_lshlrev_b32_e32 v0, 1, v0
	v_lshl_add_u64 v[2:3], v[2:3], 0, v[0:1]
	global_load_dwordx4 v[102:105], v[2:3], off offset:128
	v_subrev_u32_e32 v143, s84, v2
	v_add_u32_e32 v143, 128, v143
	v_add_u32_e32 v4, 64, v116
	v_lshlrev_b32_e32 v10, 3, v8
	v_ashrrev_i32_e32 v5, 31, v4
	s_and_saveexec_b64 s[4:5], vcc
	s_xor_b64 s[4:5], exec, s[4:5]
	v_lshlrev_b64 v[2:3], 6, v[4:5]
	v_lshl_add_u64 v[2:3], s[14:15], 0, v[2:3]
	v_mov_b32_e32 v4, v118
	v_mov_b32_e32 v5, v1
	s_movk_i32 s16, 0xff80
	v_lshl_add_u64 v[2:3], v[4:5], 1, v[2:3]
	s_mov_b32 s17, -1
	v_lshl_add_u64 v[2:3], v[2:3], 0, s[16:17]
	s_andn2_saveexec_b64 s[4:5], s[4:5]
	v_mov_b64_e32 v[2:3], s[12:13]
	v_mad_i64_i32 v[2:3], s[16:17], v4, s61, v[2:3]
	v_lshl_add_u64 v[2:3], v[118:119], 1, v[2:3]
	s_or_b64 exec, exec, s[4:5]
	global_load_dwordx4 v[98:101], v[2:3], off
	v_subrev_u32_e32 v208, s84, v2
	s_and_saveexec_b64 s[4:5], s[2:3]
	s_xor_b64 s[2:3], exec, s[4:5]
	v_lshlrev_b32_e32 v122, 3, v9
	s_or_saveexec_b64 s[4:5], s[2:3]
	s_waitcnt vmcnt(16)
	v_mov_b32_e32 v108, v1
	v_mov_b32_e32 v109, v1
	v_mov_b64_e32 v[106:107], v[108:109]
	s_xor_b64 exec, exec, s[4:5]
	s_cbranch_execz .LBB0_599
	v_add_u32_e32 v4, 64, v120
	v_cmp_lt_i32_e64 s[2:3], 7, v9
	v_ashrrev_i32_e32 v5, 31, v4
	s_and_saveexec_b64 s[16:17], s[2:3]
	s_xor_b64 s[2:3], exec, s[16:17]
	v_lshlrev_b64 v[2:3], 6, v[4:5]
	v_lshl_add_u64 v[2:3], s[14:15], 0, v[2:3]
	v_mov_b32_e32 v123, v1
	s_movk_i32 s16, 0xff80
	v_lshl_add_u64 v[2:3], v[122:123], 1, v[2:3]
	s_mov_b32 s17, -1
	v_lshl_add_u64 v[2:3], v[2:3], 0, s[16:17]
	s_andn2_saveexec_b64 s[2:3], s[2:3]
	v_mov_b64_e32 v[2:3], s[12:13]
	v_mad_i64_i32 v[2:3], s[16:17], v4, s61, v[2:3]
	v_ashrrev_i32_e32 v123, 31, v122
	v_lshl_add_u64 v[2:3], v[122:123], 1, v[2:3]
	s_or_b64 exec, exec, s[2:3]
	global_load_dwordx4 v[106:109], v[2:3], off
	v_subrev_u32_e32 v234, s84, v2
; #define MFMA(a, b, c) __builtin_amdgcn_mfma_f32_32x32x16_bf16((a), (b), (c), 0, 0, 0)
; template <int DQK>
; DI void attn_tile(const u16* __restrict__ q, int ldq, int qpos0, const Seg& s0, const Seg& s1, int nseg, bool has_sink,
;                   float sinkl2, u16* __restrict__ out, int ldo, char* lds) {
;     ...
;   f32x16 o0 = zero16(), o1 = zero16();
;   float m = -1e30f, l = 0.f;
;     ...
;   auto compute = [&](int i) {
;     const Seg& sg = (i < nt0) ? s0 : s1;
;     const int off = ((i < nt0) ? i : i - nt0) << 6;
;     f32x16 sa = zero16(), sb = zero16();
; #pragma unroll
;     for (int ks = 0; ks < NKS; ++ks) {
;       bf16x8 a0 = *(const bf16x8*)(Ks + r * KST + ks * 16 + 8 * h);
;       bf16x8 a1 = *(const bf16x8*)(Ks + (32 + r) * KST + ks * 16 + 8 * h);
;       sa = MFMA(a0, qf[ks], sa);
;       sb = MFMA(a1, qf[ks], sb);
;     }
;     ...
;   ATT_LOADX(0, kreg0, kreg1, vreg0);
;   ATT_LOADX(1, krgB0, krgB1, vrgB0);
;   for (int i = 0; i < NT; i += 2) {
;     __syncthreads();
;     ATT_STOREX(kreg0, kreg1, vreg0);
;     __syncthreads();
;     if (i + 2 < NT) ATT_LOADX(i + 2, kreg0, kreg1, vreg0);
;     compute(i);
.LBB0_599:
	s_or_b64 exec, exec, s[4:5]
	v_add_u32_e32 v4, 64, v117
	v_mov_b64_e32 v[2:3], s[12:13]
	v_mad_i64_i32 v[2:3], s[2:3], v4, s61, v[2:3]
	v_lshl_add_u64 v[2:3], v[2:3], 0, v[0:1]
	global_load_dwordx4 v[110:113], v[2:3], off offset:128
	v_subrev_u32_e32 v235, s84, v2
	v_add_u32_e32 v235, 128, v235
	s_movk_i32 s4, 0xd0
	v_lshlrev_b32_e32 v5, 1, v10
	v_lshlrev_b32_e32 v114, 2, v8
	v_lshrrev_b32_e32 v2, 2, v7
	v_mad_u32_u24 v130, v6, s4, v5
	v_and_b32_e32 v6, 64, v209
	v_and_or_b32 v2, v2, 3, v114
	s_add_u32 s23, s12, 0x80
	v_mul_lo_u32 v4, v116, s4
	v_xor_b32_e32 v5, 32, v209
	v_add_u32_e32 v6, 64, v6
	v_mul_u32_u24_e32 v2, 0xc0, v2
	v_lshlrev_b32_e32 v3, 1, v7
	s_addc_u32 s24, s13, 0
	v_lshl_add_u32 v121, v118, 1, v4
	v_mul_lo_u32 v4, v120, s4
	s_movk_i32 s2, 0xc0
	v_cmp_lt_i32_e64 s[4:5], v5, v6
	v_and_or_b32 v2, v3, 32, v2
	v_and_b32_e32 v3, 24, v11
	s_add_u32 s25, s8, 0x80
	v_lshl_add_u32 v129, v122, 1, v4
	v_mul_lo_u32 v4, v117, s2
	v_cndmask_b32_e64 v5, v209, v5, s[4:5]
	v_mov_b32_e32 v128, 0
	s_mov_b32 s22, 3
	s_addc_u32 s26, s9, 0
	v_ashrrev_i32_e32 v123, 31, v122
	v_mov_b32_e32 v124, v118
	v_mov_b32_e32 v125, v1
	v_cmp_lt_i32_e64 s[2:3], 7, v9
	v_mov_b32_e32 v126, v122
	v_mov_b32_e32 v127, v1
	v_lshlrev_b32_e32 v131, 2, v5
	v_mov_b32_e32 v134, 0xf149f2ca
	v_add_u32_e32 v132, v0, v4
	v_add_u32_e32 v133, v2, v3
	v_mov_b32_e32 v2, 0
	v_mov_b32_e32 v3, v128
	v_mov_b32_e32 v4, v128
	v_mov_b32_e32 v5, v128
	v_mov_b32_e32 v6, v128
	v_mov_b32_e32 v7, v128
	v_mov_b32_e32 v8, v128
	v_mov_b32_e32 v9, v128
	v_mov_b32_e32 v10, v128
	v_mov_b32_e32 v11, v128
	v_mov_b32_e32 v12, v128
	v_mov_b32_e32 v13, v128
	v_mov_b32_e32 v14, v128
	v_mov_b32_e32 v15, v128
	v_mov_b32_e32 v16, v128
	v_mov_b32_e32 v17, v128
	v_mov_b32_e32 v18, 0
	v_mov_b32_e32 v19, v128
	v_mov_b32_e32 v20, v128
	v_mov_b32_e32 v21, v128
	v_mov_b32_e32 v22, v128
	v_mov_b32_e32 v23, v128
	v_mov_b32_e32 v24, v128
	v_mov_b32_e32 v25, v128
	v_mov_b32_e32 v26, v128
	v_mov_b32_e32 v27, v128
	v_mov_b32_e32 v28, v128
	v_mov_b32_e32 v29, v128
	v_mov_b32_e32 v30, v128
	v_mov_b32_e32 v31, v128
	v_mov_b32_e32 v32, v128
	v_mov_b32_e32 v33, v128
	v_sub_u32_e32 v236, v208, v138
	v_lshlrev_b32_e32 v236, 1, v236
	v_sub_u32_e32 v237, v234, v142
	v_lshlrev_b32_e32 v237, 1, v237
	s_waitcnt vmcnt(0)
	s_barrier
	ds_write_b128 v121, v[90:93]
	s_and_saveexec_b64 s[4:5], s[0:1]
	ds_write_b128 v129, v[94:97]
	s_or_b64 exec, exec, s[4:5]
	s_waitcnt lgkmcnt(0)
	s_barrier
	ds_read_b128 v[34:37], v130
	ds_read_b128 v[38:41], v130 offset:6656
	ds_read_b128 v[42:45], v130 offset:32
	s_waitcnt lgkmcnt(2)
	v_mfma_f32_32x32x16_bf16 v[50:65], v[34:37], v[66:69], 0
	ds_read_b128 v[34:37], v130 offset:6688
	s_waitcnt lgkmcnt(2)
	v_mfma_f32_32x32x16_bf16 v[218:233], v[38:41], v[66:69], 0
	ds_read_b128 v[38:41], v130 offset:64
	s_waitcnt lgkmcnt(2)
	v_mfma_f32_32x32x16_bf16 v[50:65], v[42:45], v[70:73], v[50:65]
	ds_read_b128 v[42:45], v130 offset:6720
	s_waitcnt lgkmcnt(2)
	v_mfma_f32_32x32x16_bf16 v[218:233], v[34:37], v[70:73], v[218:233]
	ds_read_b128 v[34:37], v130 offset:96
	s_waitcnt lgkmcnt(2)
	v_mfma_f32_32x32x16_bf16 v[50:65], v[38:41], v[74:77], v[50:65]
	ds_read_b128 v[38:41], v130 offset:6752
	s_waitcnt lgkmcnt(2)
	v_mfma_f32_32x32x16_bf16 v[218:233], v[42:45], v[74:77], v[218:233]
	ds_read_b128 v[42:45], v130 offset:128
	s_waitcnt lgkmcnt(2)
	v_mfma_f32_32x32x16_bf16 v[50:65], v[34:37], v[78:81], v[50:65]
	ds_read_b128 v[34:37], v130 offset:6784
	s_waitcnt lgkmcnt(2)
	v_mfma_f32_32x32x16_bf16 v[218:233], v[38:41], v[78:81], v[218:233]
	ds_read_b128 v[38:41], v130 offset:160
	s_waitcnt lgkmcnt(2)
	v_mfma_f32_32x32x16_bf16 v[50:65], v[42:45], v[82:85], v[50:65]
	ds_read_b128 v[42:45], v130 offset:6816
	s_waitcnt lgkmcnt(2)
	v_mfma_f32_32x32x16_bf16 v[218:233], v[34:37], v[82:85], v[218:233]
	s_waitcnt lgkmcnt(1)
	v_mfma_f32_32x32x16_bf16 v[50:65], v[38:41], v[86:89], v[50:65]
	s_waitcnt lgkmcnt(0)
	v_mfma_f32_32x32x16_bf16 v[218:233], v[42:45], v[86:89], v[218:233]
	s_branch .LBB0_603
.LBB0_602:
	s_add_i32 s22, s22, 2
	ds_read_b128 v[34:37], v130
	ds_read_b128 v[38:41], v130 offset:6656
	ds_read_b128 v[42:45], v130 offset:32
	s_waitcnt lgkmcnt(2)
	v_mfma_f32_32x32x16_bf16 v[50:65], v[34:37], v[66:69], 0
	ds_read_b128 v[34:37], v130 offset:6688
	v_max3_f32 v137, v184, v185, v186
	v_max3_f32 v137, v137, v187, v188
	v_max3_f32 v137, v137, v189, v190
	v_max3_f32 v137, v137, v191, v192
	s_waitcnt lgkmcnt(2)
	v_mfma_f32_32x32x16_bf16 v[218:233], v[38:41], v[66:69], 0
	ds_read_b128 v[38:41], v130 offset:64
	v_max3_f32 v137, v137, v193, v194
	v_max3_f32 v137, v137, v195, v196
	v_max3_f32 v137, v137, v197, v198
	v_max3_f32 v137, v137, v199, v146
	s_waitcnt lgkmcnt(2)
	v_mfma_f32_32x32x16_bf16 v[50:65], v[42:45], v[70:73], v[50:65]
	ds_read_b128 v[42:45], v130 offset:6720
	v_max3_f32 v137, v137, v147, v148
	v_max3_f32 v137, v137, v149, v150
	v_max3_f32 v137, v137, v151, v152
	v_max3_f32 v137, v137, v153, v154
	s_waitcnt lgkmcnt(2)
	v_mfma_f32_32x32x16_bf16 v[218:233], v[34:37], v[70:73], v[218:233]
	ds_read_b128 v[34:37], v130 offset:96
	v_max3_f32 v137, v137, v155, v156
	v_max3_f32 v137, v137, v157, v158
	v_max3_f32 v137, v137, v159, v160
	v_max3_f32 v137, v137, v161, v161
	s_waitcnt lgkmcnt(2)
	v_mfma_f32_32x32x16_bf16 v[50:65], v[38:41], v[74:77], v[50:65]
	ds_read_b128 v[38:41], v130 offset:6752
	ds_bpermute_b32 v139, v131, v137
	s_waitcnt lgkmcnt(0)
; #define MFMA(a, b, c) __builtin_amdgcn_mfma_f32_32x32x16_bf16((a), (b), (c), 0, 0, 0)
; #define ATT_VTR(p) __builtin_bit_cast(s16x4, __builtin_amdgcn_ds_read_tr16_b64_v4i16((__attribute__((address_space(3))) v4i16_t*)(p)))
; template <int DQK>
; DI void attn_tile(const u16* __restrict__ q, int ldq, int qpos0, const Seg& s0, const Seg& s1, int nseg, bool has_sink,
;                   float sinkl2, u16* __restrict__ out, int ldo, char* lds) {
;     ...
;     float mx = sa[0];
; #pragma unroll
;     for (int g = 1; g < 16; ++g) mx = fmaxf(mx, sa[g]);
; #pragma unroll
;     for (int g = 0; g < 16; ++g) mx = fmaxf(mx, sb[g]);
;     mx = fmaxf(mx, __shfl_xor(mx, 32));
;     const float mn = fmaxf(m, mx);
;     const float alpha = __builtin_amdgcn_exp2f(m - mn);
;     m = mn;
;     float ps = 0.f;
; #pragma unroll
;     for (int g = 0; g < 16; ++g) { sa[g] = __builtin_amdgcn_exp2f(sa[g] - mn); ps += sa[g]; }
; #pragma unroll
;     for (int g = 0; g < 16; ++g) { sb[g] = __builtin_amdgcn_exp2f(sb[g] - mn); ps += sb[g]; }
;     l = l * alpha + ps;
; #pragma unroll
;     for (int g = 0; g < 16; ++g) { o0[g] *= alpha; o1[g] *= alpha; }
; #pragma unroll
;     for (int kt = 0; kt < 2; ++kt) {
; #pragma unroll
;       for (int s = 0; s < 2; ++s) {
;         const f32x16& sv = kt == 0 ? sa : sb;
;         uint4 pu;
;         pu.x = pack2(sv[8 * s + 0], sv[8 * s + 1]); pu.y = pack2(sv[8 * s + 2], sv[8 * s + 3]);
;         pu.z = pack2(sv[8 * s + 4], sv[8 * s + 5]); pu.w = pack2(sv[8 * s + 6], sv[8 * s + 7]);
;         bf16x8 pf = __builtin_bit_cast(bf16x8, pu);
;         const lds_cptr vp = vp0 + (kt * 32 + 16 * s) * (VST * 2);
;         {
;           s16x4 lo = ATT_VTR(vp);
;           s16x4 hi = ATT_VTR(vp + 8 * VST * 2);
;           bf16x8 vf = __builtin_shufflevector(lo, hi, 0, 1, 2, 3, 4, 5, 6, 7);
;           o0 = MFMA(vf, pf, o0);
;         }
;         {
;           s16x4 lo = ATT_VTR(vp + 64);
;           s16x4 hi = ATT_VTR(vp + 8 * VST * 2 + 64);
;           bf16x8 vf = __builtin_shufflevector(lo, hi, 0, 1, 2, 3, 4, 5, 6, 7);
;           o1 = MFMA(vf, pf, o1);
;         }
;       }
;     }
;   };
	v_max3_f32 v134, v135, v137, v139
	v_sub_f32_e32 v141, v135, v134
	v_mfma_f32_32x32x16_bf16 v[218:233], v[42:45], v[74:77], v[218:233]
	ds_read_b128 v[42:45], v130 offset:128
	v_exp_f32_e32 v140, v141
	v_mov_b32_e32 v144, v134
	v_mov_b32_e32 v145, v134
	v_sub_f32_e32 v184, v184, v134
	v_mfma_f32_32x32x16_bf16 v[50:65], v[34:37], v[78:81], v[50:65]
	ds_read_b128 v[34:37], v130 offset:6784
	v_sub_f32_e32 v185, v185, v134
	v_sub_f32_e32 v186, v186, v134
	v_sub_f32_e32 v187, v187, v134
	v_sub_f32_e32 v188, v188, v134
	v_mfma_f32_32x32x16_bf16 v[218:233], v[38:41], v[78:81], v[218:233]
	ds_read_b128 v[38:41], v130 offset:160
	v_sub_f32_e32 v189, v189, v134
	v_sub_f32_e32 v190, v190, v134
	v_sub_f32_e32 v191, v191, v134
	v_exp_f32_e32 v184, v184
	s_waitcnt lgkmcnt(2)
	v_mfma_f32_32x32x16_bf16 v[50:65], v[42:45], v[82:85], v[50:65]
	ds_read_b128 v[42:45], v130 offset:6816
	v_sub_f32_e32 v192, v192, v134
	v_sub_f32_e32 v193, v193, v134
	v_sub_f32_e32 v194, v194, v134
	v_sub_f32_e32 v195, v195, v134
	s_waitcnt lgkmcnt(2)
	v_mfma_f32_32x32x16_bf16 v[218:233], v[34:37], v[82:85], v[218:233]
	v_exp_f32_e32 v185, v185
	v_sub_f32_e32 v196, v196, v134
	v_sub_f32_e32 v197, v197, v134
	v_sub_f32_e32 v198, v198, v134
	s_waitcnt lgkmcnt(1)
	v_mfma_f32_32x32x16_bf16 v[50:65], v[38:41], v[86:89], v[50:65]
	v_sub_f32_e32 v199, v199, v134
	v_exp_f32_e32 v186, v186
	v_sub_f32_e32 v146, v146, v134
	v_sub_f32_e32 v147, v147, v134
	s_waitcnt lgkmcnt(0)
	v_mfma_f32_32x32x16_bf16 v[218:233], v[42:45], v[86:89], v[218:233]
	ds_read_b64_tr_b16 v[46:47], v133 offset:46080
	ds_read_b64_tr_b16 v[48:49], v133 offset:47616
	ds_read_b64_tr_b16 v[200:201], v133 offset:46144
	ds_read_b64_tr_b16 v[202:203], v133 offset:47680
	ds_read_b64_tr_b16 v[204:205], v133 offset:49152
	ds_read_b64_tr_b16 v[206:207], v133 offset:50688
	v_sub_f32_e32 v148, v148, v134
	v_sub_f32_e32 v149, v149, v134
	v_exp_f32_e32 v187, v187
	v_sub_f32_e32 v150, v150, v134
	v_sub_f32_e32 v151, v151, v134
	v_sub_f32_e32 v152, v152, v134
	v_sub_f32_e32 v153, v153, v134
	v_exp_f32_e32 v188, v188
	v_mul_f32_e32 v33, v140, v33
	v_mul_f32_e32 v32, v140, v32
	v_mul_f32_e32 v31, v140, v31
	v_mul_f32_e32 v30, v140, v30
	v_exp_f32_e32 v189, v189
	v_mul_f32_e32 v29, v140, v29
	v_mul_f32_e32 v28, v140, v28
	v_mul_f32_e32 v27, v140, v27
	v_mul_f32_e32 v26, v140, v26
	v_exp_f32_e32 v190, v190
	v_mul_f32_e32 v25, v140, v25
	v_mul_f32_e32 v24, v140, v24
	v_mul_f32_e32 v23, v140, v23
	v_mul_f32_e32 v22, v140, v22
	v_exp_f32_e32 v191, v191
	v_mul_f32_e32 v21, v140, v21
	v_mul_f32_e32 v20, v140, v20
	v_mul_f32_e32 v19, v140, v19
	v_mul_f32_e32 v18, v140, v18
	v_exp_f32_e32 v192, v192
	v_sub_f32_e32 v154, v154, v134
	v_sub_f32_e32 v155, v155, v134
	v_sub_f32_e32 v156, v156, v134
	v_sub_f32_e32 v157, v157, v134
	v_sub_f32_e32 v158, v158, v134
	v_exp_f32_e32 v193, v193
	v_sub_f32_e32 v159, v159, v134
	v_sub_f32_e32 v160, v160, v134
	v_sub_f32_e32 v161, v161, v134
	v_mul_f32_e32 v17, v140, v17
	v_mul_f32_e32 v16, v140, v16
	v_exp_f32_e32 v194, v194
	v_mul_f32_e32 v15, v140, v15
	v_mul_f32_e32 v14, v140, v14
	v_mul_f32_e32 v13, v140, v13
	v_mul_f32_e32 v12, v140, v12
	v_mul_f32_e32 v11, v140, v11
	v_exp_f32_e32 v195, v195
	v_mul_f32_e32 v10, v140, v10
	v_mul_f32_e32 v9, v140, v9
	v_mul_f32_e32 v8, v140, v8
	v_mul_f32_e32 v7, v140, v7
	v_mul_f32_e32 v6, v140, v6
	v_exp_f32_e32 v196, v196
	v_mul_f32_e32 v5, v140, v5
	v_mul_f32_e32 v4, v140, v4
	v_mul_f32_e32 v3, v140, v3
	v_mul_f32_e32 v2, v140, v2
	v_add_f32_e32 v238, v184, v185
	v_exp_f32_e32 v197, v197
	v_add_f32_e32 v238, v238, v186
	v_add_f32_e32 v238, v238, v187
	v_add_f32_e32 v238, v238, v188
	v_add_f32_e32 v238, v238, v189
	v_add_f32_e32 v238, v238, v190
	v_exp_f32_e32 v198, v198
	v_add_f32_e32 v238, v238, v191
	v_cvt_pk_bf16_f32 v184, v184, v185
	v_cvt_pk_bf16_f32 v185, v186, v187
	v_cvt_pk_bf16_f32 v186, v188, v189
	v_cvt_pk_bf16_f32 v187, v190, v191
	v_exp_f32_e32 v199, v199
	s_nop 0
	s_waitcnt lgkmcnt(4)
	v_mfma_f32_32x32x16_bf16 v[18:33], v[46:49], v[184:187], v[18:33]
	ds_read_b64_tr_b16 v[46:47], v133 offset:49216
	ds_read_b64_tr_b16 v[48:49], v133 offset:50752
	s_waitcnt lgkmcnt(4)
	v_mfma_f32_32x32x16_bf16 v[2:17], v[200:203], v[184:187], v[2:17]
	ds_read_b64_tr_b16 v[200:201], v133 offset:52224
	ds_read_b64_tr_b16 v[202:203], v133 offset:53760
	v_exp_f32_e32 v146, v146
	v_add_f32_e32 v238, v238, v192
	v_add_f32_e32 v238, v238, v193
	v_exp_f32_e32 v147, v147
	v_add_f32_e32 v238, v238, v194
	v_add_f32_e32 v238, v238, v195
	v_exp_f32_e32 v148, v148
	v_add_f32_e32 v238, v238, v196
	v_add_f32_e32 v238, v238, v197
	v_exp_f32_e32 v149, v149
	v_add_f32_e32 v238, v238, v198
	v_add_f32_e32 v238, v238, v199
	v_exp_f32_e32 v150, v150
	v_cvt_pk_bf16_f32 v188, v192, v193
	v_cvt_pk_bf16_f32 v189, v194, v195
	v_exp_f32_e32 v151, v151
	v_cvt_pk_bf16_f32 v190, v196, v197
	v_cvt_pk_bf16_f32 v191, v198, v199
	v_exp_f32_e32 v152, v152
	v_exp_f32_e32 v153, v153
	s_nop 0
	s_waitcnt lgkmcnt(4)
	v_mfma_f32_32x32x16_bf16 v[18:33], v[204:207], v[188:191], v[18:33]
	ds_read_b64_tr_b16 v[204:205], v133 offset:52288
	ds_read_b64_tr_b16 v[206:207], v133 offset:53824
	s_waitcnt lgkmcnt(4)
	v_mfma_f32_32x32x16_bf16 v[2:17], v[46:49], v[188:191], v[2:17]
	ds_read_b64_tr_b16 v[46:47], v133 offset:55296
	ds_read_b64_tr_b16 v[48:49], v133 offset:56832
	v_exp_f32_e32 v154, v154
	v_add_f32_e32 v238, v238, v146
	v_add_f32_e32 v238, v238, v147
	v_exp_f32_e32 v155, v155
	v_add_f32_e32 v238, v238, v148
	v_add_f32_e32 v238, v238, v149
	v_exp_f32_e32 v156, v156
	v_add_f32_e32 v238, v238, v150
	v_add_f32_e32 v238, v238, v151
	v_exp_f32_e32 v157, v157
	v_add_f32_e32 v238, v238, v152
	v_add_f32_e32 v238, v238, v153
	v_exp_f32_e32 v158, v158
	v_cvt_pk_bf16_f32 v146, v146, v147
	v_cvt_pk_bf16_f32 v147, v148, v149
	v_exp_f32_e32 v159, v159
	v_cvt_pk_bf16_f32 v148, v150, v151
	v_cvt_pk_bf16_f32 v149, v152, v153
	v_exp_f32_e32 v160, v160
	v_exp_f32_e32 v161, v161
	s_nop 0
	s_waitcnt lgkmcnt(4)
	v_mfma_f32_32x32x16_bf16 v[18:33], v[200:203], v[146:149], v[18:33]
	ds_read_b64_tr_b16 v[200:201], v133 offset:55360
	ds_read_b64_tr_b16 v[202:203], v133 offset:56896
	s_waitcnt lgkmcnt(4)
	v_mfma_f32_32x32x16_bf16 v[2:17], v[204:207], v[146:149], v[2:17]
	v_add_f32_e32 v238, v238, v154
	v_add_f32_e32 v238, v238, v155
	v_add_f32_e32 v238, v238, v156
	v_add_f32_e32 v238, v238, v157
	v_add_f32_e32 v238, v238, v158
	v_add_f32_e32 v238, v238, v159
	v_add_f32_e32 v238, v238, v160
	v_add_f32_e32 v238, v238, v161
	v_cvt_pk_bf16_f32 v150, v154, v155
	v_cvt_pk_bf16_f32 v151, v156, v157
	v_cvt_pk_bf16_f32 v152, v158, v159
	v_cvt_pk_bf16_f32 v153, v160, v161
	s_nop 0
	s_waitcnt lgkmcnt(2)
	v_mfma_f32_32x32x16_bf16 v[18:33], v[46:49], v[150:153], v[18:33]
	s_waitcnt lgkmcnt(0)
	v_mfma_f32_32x32x16_bf16 v[2:17], v[200:203], v[150:153], v[2:17]
	v_fma_f32 v128, v136, v140, v238
	s_cmpk_lt_u32 s27, 0x42
	s_cbranch_scc0 .LBB0_727
; template <int DQK>
; DI void attn_tile(const u16* __restrict__ q, int ldq, int qpos0, const Seg& s0, const Seg& s1, int nseg, bool has_sink,
;                   float sinkl2, u16* __restrict__ out, int ldo, char* lds) {
;     ...
;   for (int i = 0; i < NT; i += 2) {
;     __syncthreads();
;     ATT_STOREX(kreg0, kreg1, vreg0);
;     __syncthreads();
;     if (i + 2 < NT) ATT_LOADX(i + 2, kreg0, kreg1, vreg0);
;     compute(i);
;     __syncthreads();
;     ATT_STOREX(krgB0, krgB1, vrgB0);
;     __syncthreads();
;     if (i + 3 < NT) ATT_LOADX(i + 3, krgB0, krgB1, vrgB0);
.LBB0_603:
	s_nop 0
	s_waitcnt vmcnt(0)
	ds_write_b128 v121, v[98:101] offset:32768
	s_and_saveexec_b64 s[4:5], s[0:1]
	ds_write_b128 v129, v[106:109] offset:32768
	s_or_b64 exec, exec, s[4:5]
	s_add_i32 s27, s22, -3
	s_cmpk_gt_u32 s27, 0x41
	s_waitcnt vmcnt(2)
	ds_write_b128 v132, v[102:105] offset:13312
	s_waitcnt lgkmcnt(0)
	s_barrier
	s_cbranch_scc1 .LBB0_617
	s_cmp_eq_u32 s27, 62
	s_cbranch_scc0 .Lmla_e_nosw
	s_sub_u32 s16, s10, s14
	s_lshr_b32 s16, s16, 6
	s_sub_u32 s16, s16, 0x1000
	v_lshrrev_b32_e32 v34, 7, v236
	v_mul_lo_u32 v34, v34, s16
	v_add_u32_e32 v138, v138, v34
	v_lshrrev_b32_e32 v34, 7, v237
	v_mul_lo_u32 v34, v34, s16
	v_add_u32_e32 v142, v142, v34
	s_mul_i32 s17, s16, 0x480
	v_add_u32_e32 v143, s17, v143
.Lmla_e_nosw:
	v_add_u32_e32 v138, v138, v236
	v_add_u32_e32 v142, v142, v237
	v_add_u32_e32 v143, 0x24000, v143
	global_load_dwordx4 v[90:93], v138, s[84:85]
	s_and_saveexec_b64 s[16:17], s[0:1]
	global_load_dwordx4 v[94:97], v142, s[84:85]
	s_or_b64 exec, exec, s[16:17]
	global_load_dwordx4 v[102:105], v143, s[84:85]
.LBB0_617:
	ds_read_b128 v[34:37], v130 offset:32768
	ds_read_b128 v[38:41], v130 offset:39424
	ds_read_b128 v[42:45], v130 offset:32800
	s_waitcnt lgkmcnt(2)
	v_mfma_f32_32x32x16_bf16 v[184:199], v[34:37], v[66:69], 0
	ds_read_b128 v[34:37], v130 offset:39456
	v_max3_f32 v137, v50, v51, v52
	v_max3_f32 v137, v137, v53, v54
	v_max3_f32 v137, v137, v55, v56
	v_max3_f32 v137, v137, v57, v58
	s_waitcnt lgkmcnt(2)
	v_mfma_f32_32x32x16_bf16 v[146:161], v[38:41], v[66:69], 0
	ds_read_b128 v[38:41], v130 offset:32832
	v_max3_f32 v137, v137, v59, v60
	v_max3_f32 v137, v137, v61, v62
	v_max3_f32 v137, v137, v63, v64
	v_max3_f32 v137, v137, v65, v218
	s_waitcnt lgkmcnt(2)
	v_mfma_f32_32x32x16_bf16 v[184:199], v[42:45], v[70:73], v[184:199]
	ds_read_b128 v[42:45], v130 offset:39488
	v_max3_f32 v137, v137, v219, v220
	v_max3_f32 v137, v137, v221, v222
	v_max3_f32 v137, v137, v223, v224
	v_max3_f32 v137, v137, v225, v226
	s_waitcnt lgkmcnt(2)
	v_mfma_f32_32x32x16_bf16 v[146:161], v[34:37], v[70:73], v[146:161]
	ds_read_b128 v[34:37], v130 offset:32864
	v_max3_f32 v137, v137, v227, v228
	v_max3_f32 v137, v137, v229, v230
	v_max3_f32 v137, v137, v231, v232
	v_max3_f32 v137, v137, v233, v233
	s_waitcnt lgkmcnt(2)
	v_mfma_f32_32x32x16_bf16 v[184:199], v[38:41], v[74:77], v[184:199]
	ds_read_b128 v[38:41], v130 offset:39520
	ds_bpermute_b32 v139, v131, v137
	s_waitcnt lgkmcnt(0)
	v_max3_f32 v135, v134, v137, v139
	v_sub_f32_e32 v141, v134, v135
	v_mfma_f32_32x32x16_bf16 v[146:161], v[42:45], v[74:77], v[146:161]
	ds_read_b128 v[42:45], v130 offset:32896
	v_exp_f32_e32 v140, v141
	v_mov_b32_e32 v144, v135
	v_mov_b32_e32 v145, v135
	v_sub_f32_e32 v50, v50, v135
	v_mfma_f32_32x32x16_bf16 v[184:199], v[34:37], v[78:81], v[184:199]
	ds_read_b128 v[34:37], v130 offset:39552
	v_sub_f32_e32 v51, v51, v135
	v_sub_f32_e32 v52, v52, v135
	v_sub_f32_e32 v53, v53, v135
	v_sub_f32_e32 v54, v54, v135
	v_mfma_f32_32x32x16_bf16 v[146:161], v[38:41], v[78:81], v[146:161]
	ds_read_b128 v[38:41], v130 offset:32928
	v_sub_f32_e32 v55, v55, v135
	v_sub_f32_e32 v56, v56, v135
	v_sub_f32_e32 v57, v57, v135
	v_exp_f32_e32 v50, v50
	s_waitcnt lgkmcnt(2)
	v_mfma_f32_32x32x16_bf16 v[184:199], v[42:45], v[82:85], v[184:199]
	ds_read_b128 v[42:45], v130 offset:39584
	v_sub_f32_e32 v58, v58, v135
	v_sub_f32_e32 v59, v59, v135
	v_sub_f32_e32 v60, v60, v135
	v_sub_f32_e32 v61, v61, v135
	s_waitcnt lgkmcnt(2)
	v_mfma_f32_32x32x16_bf16 v[146:161], v[34:37], v[82:85], v[146:161]
	v_exp_f32_e32 v51, v51
	v_sub_f32_e32 v62, v62, v135
	v_sub_f32_e32 v63, v63, v135
	v_sub_f32_e32 v64, v64, v135
	s_waitcnt lgkmcnt(1)
	v_mfma_f32_32x32x16_bf16 v[184:199], v[38:41], v[86:89], v[184:199]
	v_sub_f32_e32 v65, v65, v135
	v_exp_f32_e32 v52, v52
	v_sub_f32_e32 v218, v218, v135
	v_sub_f32_e32 v219, v219, v135
	s_waitcnt lgkmcnt(0)
; #define MFMA(a, b, c) __builtin_amdgcn_mfma_f32_32x32x16_bf16((a), (b), (c), 0, 0, 0)
; #define ATT_VTR(p) __builtin_bit_cast(s16x4, __builtin_amdgcn_ds_read_tr16_b64_v4i16((__attribute__((address_space(3))) v4i16_t*)(p)))
; template <int DQK>
; DI void attn_tile(const u16* __restrict__ q, int ldq, int qpos0, const Seg& s0, const Seg& s1, int nseg, bool has_sink,
;                   float sinkl2, u16* __restrict__ out, int ldo, char* lds) {
;     ...
;     for (int g = 0; g < 16; ++g) { sa[g] = __builtin_amdgcn_exp2f(sa[g] - mn); ps += sa[g]; }
; #pragma unroll
;     for (int g = 0; g < 16; ++g) { sb[g] = __builtin_amdgcn_exp2f(sb[g] - mn); ps += sb[g]; }
;     l = l * alpha + ps;
; #pragma unroll
;     for (int g = 0; g < 16; ++g) { o0[g] *= alpha; o1[g] *= alpha; }
; #pragma unroll
;     for (int kt = 0; kt < 2; ++kt) {
; #pragma unroll
;       for (int s = 0; s < 2; ++s) {
;         const f32x16& sv = kt == 0 ? sa : sb;
;         uint4 pu;
;         pu.x = pack2(sv[8 * s + 0], sv[8 * s + 1]); pu.y = pack2(sv[8 * s + 2], sv[8 * s + 3]);
;         pu.z = pack2(sv[8 * s + 4], sv[8 * s + 5]); pu.w = pack2(sv[8 * s + 6], sv[8 * s + 7]);
;         bf16x8 pf = __builtin_bit_cast(bf16x8, pu);
;         const lds_cptr vp = vp0 + (kt * 32 + 16 * s) * (VST * 2);
;         {
;           s16x4 lo = ATT_VTR(vp);
;           s16x4 hi = ATT_VTR(vp + 8 * VST * 2);
;           bf16x8 vf = __builtin_shufflevector(lo, hi, 0, 1, 2, 3, 4, 5, 6, 7);
;           o0 = MFMA(vf, pf, o0);
;         }
;         {
;           s16x4 lo = ATT_VTR(vp + 64);
;           s16x4 hi = ATT_VTR(vp + 8 * VST * 2 + 64);
;           bf16x8 vf = __builtin_shufflevector(lo, hi, 0, 1, 2, 3, 4, 5, 6, 7);
;           o1 = MFMA(vf, pf, o1);
;         }
;       }
;     }
;   };
;   ATT_LOADX(0, kreg0, kreg1, vreg0);
;   ATT_LOADX(1, krgB0, krgB1, vrgB0);
;   for (int i = 0; i < NT; i += 2) {
;     __syncthreads();
;     ATT_STOREX(kreg0, kreg1, vreg0);
;     __syncthreads();
;     if (i + 2 < NT) ATT_LOADX(i + 2, kreg0, kreg1, vreg0);
;     compute(i);
;     __syncthreads();
;     ATT_STOREX(krgB0, krgB1, vrgB0);
;     __syncthreads();
;     if (i + 3 < NT) ATT_LOADX(i + 3, krgB0, krgB1, vrgB0);
;     compute(i + 1);
	v_mfma_f32_32x32x16_bf16 v[146:161], v[42:45], v[86:89], v[146:161]
	ds_read_b64_tr_b16 v[46:47], v133 offset:13312
	ds_read_b64_tr_b16 v[48:49], v133 offset:14848
	ds_read_b64_tr_b16 v[200:201], v133 offset:13376
	ds_read_b64_tr_b16 v[202:203], v133 offset:14912
	ds_read_b64_tr_b16 v[204:205], v133 offset:16384
	ds_read_b64_tr_b16 v[206:207], v133 offset:17920
	v_sub_f32_e32 v220, v220, v135
	v_sub_f32_e32 v221, v221, v135
	v_exp_f32_e32 v53, v53
	v_sub_f32_e32 v222, v222, v135
	v_sub_f32_e32 v223, v223, v135
	v_sub_f32_e32 v224, v224, v135
	v_sub_f32_e32 v225, v225, v135
	v_exp_f32_e32 v54, v54
	v_mul_f32_e32 v33, v140, v33
	v_mul_f32_e32 v32, v140, v32
	v_mul_f32_e32 v31, v140, v31
	v_mul_f32_e32 v30, v140, v30
	v_exp_f32_e32 v55, v55
	v_mul_f32_e32 v29, v140, v29
	v_mul_f32_e32 v28, v140, v28
	v_mul_f32_e32 v27, v140, v27
	v_mul_f32_e32 v26, v140, v26
	v_exp_f32_e32 v56, v56
	v_mul_f32_e32 v25, v140, v25
	v_mul_f32_e32 v24, v140, v24
	v_mul_f32_e32 v23, v140, v23
	v_mul_f32_e32 v22, v140, v22
	v_exp_f32_e32 v57, v57
	v_mul_f32_e32 v21, v140, v21
	v_mul_f32_e32 v20, v140, v20
	v_mul_f32_e32 v19, v140, v19
	v_mul_f32_e32 v18, v140, v18
	v_exp_f32_e32 v58, v58
	v_sub_f32_e32 v226, v226, v135
	v_sub_f32_e32 v227, v227, v135
	v_sub_f32_e32 v228, v228, v135
	v_sub_f32_e32 v229, v229, v135
	v_sub_f32_e32 v230, v230, v135
	v_exp_f32_e32 v59, v59
	v_sub_f32_e32 v231, v231, v135
	v_sub_f32_e32 v232, v232, v135
	v_sub_f32_e32 v233, v233, v135
	v_mul_f32_e32 v17, v140, v17
	v_mul_f32_e32 v16, v140, v16
	v_exp_f32_e32 v60, v60
	v_mul_f32_e32 v15, v140, v15
	v_mul_f32_e32 v14, v140, v14
	v_mul_f32_e32 v13, v140, v13
	v_mul_f32_e32 v12, v140, v12
	v_mul_f32_e32 v11, v140, v11
	v_exp_f32_e32 v61, v61
	v_mul_f32_e32 v10, v140, v10
	v_mul_f32_e32 v9, v140, v9
	v_mul_f32_e32 v8, v140, v8
	v_mul_f32_e32 v7, v140, v7
	v_mul_f32_e32 v6, v140, v6
	v_exp_f32_e32 v62, v62
	v_mul_f32_e32 v5, v140, v5
	v_mul_f32_e32 v4, v140, v4
	v_mul_f32_e32 v3, v140, v3
	v_mul_f32_e32 v2, v140, v2
	v_add_f32_e32 v238, v50, v51
	v_exp_f32_e32 v63, v63
	v_add_f32_e32 v238, v238, v52
	v_add_f32_e32 v238, v238, v53
	v_add_f32_e32 v238, v238, v54
	v_add_f32_e32 v238, v238, v55
	v_add_f32_e32 v238, v238, v56
	v_exp_f32_e32 v64, v64
	v_add_f32_e32 v238, v238, v57
	v_cvt_pk_bf16_f32 v50, v50, v51
	v_cvt_pk_bf16_f32 v51, v52, v53
	v_cvt_pk_bf16_f32 v52, v54, v55
	v_cvt_pk_bf16_f32 v53, v56, v57
	v_exp_f32_e32 v65, v65
	s_nop 0
	s_waitcnt lgkmcnt(4)
	v_mfma_f32_32x32x16_bf16 v[18:33], v[46:49], v[50:53], v[18:33]
	ds_read_b64_tr_b16 v[46:47], v133 offset:16448
	ds_read_b64_tr_b16 v[48:49], v133 offset:17984
	s_waitcnt lgkmcnt(4)
	v_mfma_f32_32x32x16_bf16 v[2:17], v[200:203], v[50:53], v[2:17]
	ds_read_b64_tr_b16 v[200:201], v133 offset:19456
	ds_read_b64_tr_b16 v[202:203], v133 offset:20992
	v_exp_f32_e32 v218, v218
	v_add_f32_e32 v238, v238, v58
	v_add_f32_e32 v238, v238, v59
	v_exp_f32_e32 v219, v219
	v_add_f32_e32 v238, v238, v60
	v_add_f32_e32 v238, v238, v61
	v_exp_f32_e32 v220, v220
	v_add_f32_e32 v238, v238, v62
	v_add_f32_e32 v238, v238, v63
	v_exp_f32_e32 v221, v221
	v_add_f32_e32 v238, v238, v64
	v_add_f32_e32 v238, v238, v65
	v_exp_f32_e32 v222, v222
	v_cvt_pk_bf16_f32 v54, v58, v59
	v_cvt_pk_bf16_f32 v55, v60, v61
	v_exp_f32_e32 v223, v223
	v_cvt_pk_bf16_f32 v56, v62, v63
	v_cvt_pk_bf16_f32 v57, v64, v65
	v_exp_f32_e32 v224, v224
	v_exp_f32_e32 v225, v225
	s_nop 0
	s_waitcnt lgkmcnt(4)
	v_mfma_f32_32x32x16_bf16 v[18:33], v[204:207], v[54:57], v[18:33]
	ds_read_b64_tr_b16 v[204:205], v133 offset:19520
	ds_read_b64_tr_b16 v[206:207], v133 offset:21056
	s_waitcnt lgkmcnt(4)
	v_mfma_f32_32x32x16_bf16 v[2:17], v[46:49], v[54:57], v[2:17]
	ds_read_b64_tr_b16 v[46:47], v133 offset:22528
	ds_read_b64_tr_b16 v[48:49], v133 offset:24064
	v_exp_f32_e32 v226, v226
	v_add_f32_e32 v238, v238, v218
	v_add_f32_e32 v238, v238, v219
	v_exp_f32_e32 v227, v227
	v_add_f32_e32 v238, v238, v220
	v_add_f32_e32 v238, v238, v221
	v_exp_f32_e32 v228, v228
	v_add_f32_e32 v238, v238, v222
	v_add_f32_e32 v238, v238, v223
	v_exp_f32_e32 v229, v229
	v_add_f32_e32 v238, v238, v224
	v_add_f32_e32 v238, v238, v225
	v_exp_f32_e32 v230, v230
	v_cvt_pk_bf16_f32 v218, v218, v219
	v_cvt_pk_bf16_f32 v219, v220, v221
	v_exp_f32_e32 v231, v231
	v_cvt_pk_bf16_f32 v220, v222, v223
	v_cvt_pk_bf16_f32 v221, v224, v225
	v_exp_f32_e32 v232, v232
	v_exp_f32_e32 v233, v233
	s_nop 0
	s_waitcnt lgkmcnt(4)
	v_mfma_f32_32x32x16_bf16 v[18:33], v[200:203], v[218:221], v[18:33]
	ds_read_b64_tr_b16 v[200:201], v133 offset:22592
	ds_read_b64_tr_b16 v[202:203], v133 offset:24128
	s_waitcnt lgkmcnt(4)
	v_mfma_f32_32x32x16_bf16 v[2:17], v[204:207], v[218:221], v[2:17]
	v_add_f32_e32 v238, v238, v226
	v_add_f32_e32 v238, v238, v227
	v_add_f32_e32 v238, v238, v228
	v_add_f32_e32 v238, v238, v229
	v_add_f32_e32 v238, v238, v230
	v_add_f32_e32 v238, v238, v231
	v_add_f32_e32 v238, v238, v232
	v_add_f32_e32 v238, v238, v233
	v_cvt_pk_bf16_f32 v222, v226, v227
	v_cvt_pk_bf16_f32 v223, v228, v229
	v_cvt_pk_bf16_f32 v224, v230, v231
	v_cvt_pk_bf16_f32 v225, v232, v233
	s_nop 0
	s_waitcnt lgkmcnt(2)
	v_mfma_f32_32x32x16_bf16 v[18:33], v[46:49], v[222:225], v[18:33]
	s_waitcnt lgkmcnt(0)
	v_mfma_f32_32x32x16_bf16 v[2:17], v[200:203], v[222:225], v[2:17]
	v_fma_f32 v136, v128, v140, v238
	s_waitcnt vmcnt(0)
	ds_write_b128 v121, v[90:93]
	s_and_saveexec_b64 s[4:5], s[0:1]
	ds_write_b128 v129, v[94:97]
	s_or_b64 exec, exec, s[4:5]
	s_cmp_gt_u32 s27, 64
	ds_write_b128 v132, v[110:113] offset:46080
	s_waitcnt lgkmcnt(0)
	s_barrier
	s_cbranch_scc1 .LBB0_602
	s_cmp_eq_u32 s27, 62
	s_cbranch_scc0 .Lmla_o_nosw
	s_sub_u32 s16, s10, s14
	s_lshr_b32 s16, s16, 6
	s_sub_u32 s16, s16, 0x1000
	v_lshrrev_b32_e32 v34, 7, v236
	v_mul_lo_u32 v34, v34, s16
	v_add_u32_e32 v208, v208, v34
	v_lshrrev_b32_e32 v34, 7, v237
	v_mul_lo_u32 v34, v34, s16
	v_add_u32_e32 v234, v234, v34
	s_mul_i32 s17, s16, 0x480
	v_add_u32_e32 v235, s17, v235
.Lmla_o_nosw:
	v_add_u32_e32 v208, v208, v236
	v_add_u32_e32 v234, v234, v237
	v_add_u32_e32 v235, 0x24000, v235
	global_load_dwordx4 v[98:101], v208, s[84:85]
	s_and_saveexec_b64 s[16:17], s[0:1]
	global_load_dwordx4 v[106:109], v234, s[84:85]
	s_or_b64 exec, exec, s[16:17]
	global_load_dwordx4 v[110:113], v235, s[84:85]
	s_branch .LBB0_602
